# in-proj unit map: XCD0/1 take one of their own scan rounds in round 7, XCD2/3 take the freed cheap round (6s+2c -> 5s+3c)
# speedup vs baseline: 1.0016x; 1.0016x over previous
;     __device__ bool next(int i, Unit& u) const { const long L = (long)i * G + c; if (L >= nwg) return false; return map((int)L, u); }
;     __device__ bool next(int i, Unit& u) const {
;         const long L = (long)i * G + c;
;         if (L < nwg) return map((int)L, u);
;         const int k = (int)(L - nwg); if (k >= 64) return false;
;         u.pm = 128 + (k >> 3); u.pn = k & 7; return true;
;     }
.Lp2_map_a3:
	s_cmp_lg_u32 s86, 7
	s_cbranch_scc1 .Lp2_map_a3b
	s_lshl_b32 s50, s11, 1
	s_mov_b32 s51, 1
	s_branch .Lp2_map_fin

;     __device__ bool next(int i, Unit& u) const { const long L = (long)i * G + c; if (L >= nwg) return false; return map((int)L, u); }
;     __device__ bool next(int i, Unit& u) const {
;         const long L = (long)i * G + c;
;         if (L < nwg) return map((int)L, u);
;         const int k = (int)(L - nwg); if (k >= 64) return false;
;         u.pm = 128 + (k >> 3); u.pn = k & 7; return true;
;     }
.Lp2_map_b:
	s_cmp_gt_u32 s11, 3
	s_cbranch_scc1 .Lp2_map_c
	s_cmp_lt_u32 s86, 6
	s_cbranch_scc1 .Lp2_map_fin
	s_cmp_lg_u32 s86, 7
	s_cbranch_scc1 .Lp2_map_b6
	s_lshl_b32 s50, s11, 2
	s_add_u32 s50, s50, 3
	s_mov_b32 s51, 3
	s_branch .Lp2_map_fin
.Lp2_map_b6:
	s_lshl_b32 s50, s11, 1
	s_sub_u32 s50, s50, 4
	s_sub_u32 s51, s86, 6
	s_branch .Lp2_map_fin
